# GEMM: removed the compiler's per-unit s_waitcnt vmcnt(0) drain in the K-loop preheader of four GEMM instances (the loop's counted waits already cover every load it consumes; epilogue stores now retire
# speedup vs baseline: 1.0035x; 1.0035x over previous
; template <class Epi, class Sched, bool ALIGN_EPI = false, bool SP2 = false>
; __device__ __forceinline__ void gemm_phase(PG8_LAS unsigned char* lds, const Gemm g, const Sched& S, const Epi& E) {
;     ...
;         const bool has_next = S.next(ui + 1, nxt);
;         const char* nA = has_next ? (const char*)g.A + (size_t)nxt.pm * tstepA : cA; const char* nB = has_next ? (const char*)g.Bt + (size_t)nxt.pn * tstep : cB;
;         for (int t = 0; t < nt; t += 2) {
;             const bool last = (t == nt - 2);
;             const char* a1 = cA + (size_t)(t + 1) * kstep;
;             const char* a2 = last ? nA : cA + (size_t)(t + 2) * kstep; const char* b2 = last ? nB : cB + (size_t)(t + 2) * kstep;
;             const char* a3 = a2 + kstep; const char* b3 = b2 + kstep;
;     ...
; #pragma unroll
;         for (int a = 0; a < 2; ++a)
; #pragma unroll
;             for (int b = 0; b < 2; ++b)
; #pragma unroll
;                 for (int m = 0; m < 4; ++m)
; #pragma unroll
;                     for (int n = 0; n < 2; ++n) acc[a][b][m][n] = (f32x4){0.f, 0.f, 0.f, 0.f};
.LBB0_102:
	s_ashr_i32 s13, s12, 31
	s_lshl_b64 s[18:19], s[12:13], 19
	s_add_u32 s18, s30, s18
	s_addc_u32 s19, s31, s19
	s_and_b64 s[20:21], s[40:41], exec
	s_cselect_b32 s13, s19, s43
	s_cselect_b32 s51, s18, s42
	s_ashr_i32 s11, s10, 31
	s_lshl_b64 s[20:21], s[10:11], 19
	v_readlane_b32 s46, v254, 44
	v_readlane_b32 s47, v254, 45
	s_add_u32 s20, s46, s20
	s_addc_u32 s21, s47, s21
	s_and_b64 s[46:47], s[40:41], exec
	s_cselect_b32 s11, s21, s45
	s_cselect_b32 s52, s20, s44
	s_add_u32 s42, s42, 0x40080
	s_addc_u32 s43, s43, 0
	s_add_u32 s53, s44, 0x100
	v_mov_b32_e32 v2, 0
	s_addc_u32 s54, s45, 0
	s_mov_b32 s55, -2
	v_mov_b32_e32 v3, v2
	v_mov_b32_e32 v4, v2
	v_mov_b32_e32 v5, v2
	v_mov_b32_e32 v6, v2
	v_mov_b32_e32 v7, v2
	v_mov_b32_e32 v8, v2
	v_mov_b32_e32 v9, v2
	v_mov_b32_e32 v14, v2
	v_mov_b32_e32 v15, v2
	v_mov_b32_e32 v16, v2
	v_mov_b32_e32 v17, v2
	v_mov_b32_e32 v22, v2
	v_mov_b32_e32 v23, v2
	v_mov_b32_e32 v24, v2
	v_mov_b32_e32 v25, v2
	v_mov_b32_e32 v30, v2
	v_mov_b32_e32 v31, v2
	v_mov_b32_e32 v32, v2
	v_mov_b32_e32 v33, v2
	v_mov_b32_e32 v38, v2
	v_mov_b32_e32 v39, v2
	v_mov_b32_e32 v40, v2
	v_mov_b32_e32 v41, v2
	v_mov_b32_e32 v46, v2
	v_mov_b32_e32 v47, v2
	v_mov_b32_e32 v48, v2
	v_mov_b32_e32 v49, v2
	v_mov_b32_e32 v54, v2
	v_mov_b32_e32 v55, v2
	v_mov_b32_e32 v56, v2
	v_mov_b32_e32 v57, v2
	v_mov_b32_e32 v10, v2
	v_mov_b32_e32 v11, v2
	v_mov_b32_e32 v12, v2
	v_mov_b32_e32 v13, v2
	v_mov_b32_e32 v18, v2
	v_mov_b32_e32 v19, v2
	v_mov_b32_e32 v20, v2
	v_mov_b32_e32 v21, v2
	v_mov_b32_e32 v26, v2
	v_mov_b32_e32 v27, v2
	v_mov_b32_e32 v28, v2
	v_mov_b32_e32 v29, v2
	v_mov_b32_e32 v34, v2
	v_mov_b32_e32 v35, v2
	v_mov_b32_e32 v36, v2
	v_mov_b32_e32 v37, v2
	v_mov_b32_e32 v42, v2
	v_mov_b32_e32 v43, v2
	v_mov_b32_e32 v44, v2
	v_mov_b32_e32 v45, v2
	v_mov_b32_e32 v50, v2
	v_mov_b32_e32 v51, v2
	v_mov_b32_e32 v52, v2
	v_mov_b32_e32 v53, v2
	v_mov_b32_e32 v58, v2
	v_mov_b32_e32 v59, v2
	v_mov_b32_e32 v60, v2
	v_mov_b32_e32 v61, v2
	v_mov_b32_e32 v62, v2
	v_mov_b32_e32 v63, v2
	v_mov_b32_e32 v64, v2
	v_mov_b32_e32 v65, v2
	v_mov_b32_e32 v66, v2
	v_mov_b32_e32 v67, v2
	v_mov_b32_e32 v68, v2
	v_mov_b32_e32 v69, v2
	v_mov_b32_e32 v70, v2
	v_mov_b32_e32 v71, v2
	v_mov_b32_e32 v72, v2
	v_mov_b32_e32 v73, v2
	v_mov_b32_e32 v84, v2
	v_mov_b32_e32 v85, v2
	v_mov_b32_e32 v86, v2
	v_mov_b32_e32 v87, v2
	v_mov_b32_e32 v92, v2
	v_mov_b32_e32 v93, v2
	v_mov_b32_e32 v94, v2
	v_mov_b32_e32 v95, v2
	v_mov_b32_e32 v100, v2
	v_mov_b32_e32 v101, v2
	v_mov_b32_e32 v102, v2
	v_mov_b32_e32 v103, v2
	v_mov_b32_e32 v108, v2
	v_mov_b32_e32 v109, v2
	v_mov_b32_e32 v110, v2
	v_mov_b32_e32 v111, v2
	v_mov_b32_e32 v116, v2
	v_mov_b32_e32 v117, v2
	v_mov_b32_e32 v118, v2
	v_mov_b32_e32 v119, v2
	v_mov_b32_e32 v124, v2
	v_mov_b32_e32 v125, v2
	v_mov_b32_e32 v126, v2
	v_mov_b32_e32 v127, v2
	v_mov_b32_e32 v74, v2
	v_mov_b32_e32 v75, v2
	v_mov_b32_e32 v76, v2
	v_mov_b32_e32 v77, v2
	v_mov_b32_e32 v88, v2
	v_mov_b32_e32 v89, v2
	v_mov_b32_e32 v90, v2
	v_mov_b32_e32 v91, v2
	v_mov_b32_e32 v96, v2
	v_mov_b32_e32 v97, v2
	v_mov_b32_e32 v98, v2
	v_mov_b32_e32 v99, v2
	v_mov_b32_e32 v104, v2
	v_mov_b32_e32 v105, v2
	v_mov_b32_e32 v106, v2
	v_mov_b32_e32 v107, v2
	v_mov_b32_e32 v112, v2
	v_mov_b32_e32 v113, v2
	v_mov_b32_e32 v114, v2
	v_mov_b32_e32 v115, v2
	v_mov_b32_e32 v120, v2
	v_mov_b32_e32 v121, v2
	v_mov_b32_e32 v122, v2
	v_mov_b32_e32 v123, v2
	v_mov_b32_e32 v128, v2
	v_mov_b32_e32 v129, v2
	v_mov_b32_e32 v130, v2
	v_mov_b32_e32 v131, v2
	v_mov_b32_e32 v132, v2
	v_mov_b32_e32 v133, v2
	v_mov_b32_e32 v134, v2
	v_mov_b32_e32 v135, v2

; template <class Epi, class Sched, bool ALIGN_EPI = false, bool SP2 = false>
; __device__ __forceinline__ void gemm_phase(PG8_LAS unsigned char* lds, const Gemm g, const Sched& S, const Epi& E) {
;     ...
;         const bool has_next = S.next(ui + 1, nxt);
;         const char* nA = has_next ? (const char*)g.A + (size_t)nxt.pm * tstepA : cA; const char* nB = has_next ? (const char*)g.Bt + (size_t)nxt.pn * tstep : cB;
;         for (int t = 0; t < nt; t += 2) {
;             const bool last = (t == nt - 2);
;             const char* a1 = cA + (size_t)(t + 1) * kstep;
;             const char* a2 = last ? nA : cA + (size_t)(t + 2) * kstep; const char* b2 = last ? nB : cB + (size_t)(t + 2) * kstep;
;             const char* a3 = a2 + kstep; const char* b3 = b2 + kstep;
;     ...
; #pragma unroll
;         for (int a = 0; a < 2; ++a)
; #pragma unroll
;             for (int b = 0; b < 2; ++b)
; #pragma unroll
;                 for (int m = 0; m < 4; ++m)
; #pragma unroll
;                     for (int n = 0; n < 2; ++n) acc[a][b][m][n] = (f32x4){0.f, 0.f, 0.f, 0.f};
.LBB0_369:
	s_ashr_i32 s19, s18, 31
	s_lshl_b64 s[20:21], s[18:19], 19
	s_add_u32 s20, s30, s20
	s_addc_u32 s21, s31, s21
	s_and_b64 s[42:43], s[40:41], exec
	s_cselect_b32 s19, s21, s45
	s_cselect_b32 s52, s20, s44
	s_ashr_i32 s13, s12, 31
	s_lshl_b64 s[42:43], s[12:13], 19
	v_readlane_b32 s48, v254, 48
	v_readlane_b32 s49, v254, 49
	s_add_u32 s42, s48, s42
	s_addc_u32 s43, s49, s43
	s_and_b64 s[48:49], s[40:41], exec
	s_cselect_b32 s13, s43, s47
	s_cselect_b32 s53, s42, s46
	s_add_u32 s44, s44, 0x40080
	s_addc_u32 s45, s45, 0
	s_add_u32 s54, s46, 0x100
	v_mov_b32_e32 v2, 0
	s_addc_u32 s55, s47, 0
	s_mov_b32 s56, -2
	v_mov_b32_e32 v3, v2
	v_mov_b32_e32 v4, v2
	v_mov_b32_e32 v5, v2
	v_mov_b32_e32 v6, v2
	v_mov_b32_e32 v7, v2
	v_mov_b32_e32 v8, v2
	v_mov_b32_e32 v9, v2
	v_mov_b32_e32 v14, v2
	v_mov_b32_e32 v15, v2
	v_mov_b32_e32 v16, v2
	v_mov_b32_e32 v17, v2
	v_mov_b32_e32 v22, v2
	v_mov_b32_e32 v23, v2
	v_mov_b32_e32 v24, v2
	v_mov_b32_e32 v25, v2
	v_mov_b32_e32 v30, v2
	v_mov_b32_e32 v31, v2
	v_mov_b32_e32 v32, v2
	v_mov_b32_e32 v33, v2
	v_mov_b32_e32 v38, v2
	v_mov_b32_e32 v39, v2
	v_mov_b32_e32 v40, v2
	v_mov_b32_e32 v41, v2
	v_mov_b32_e32 v46, v2
	v_mov_b32_e32 v47, v2
	v_mov_b32_e32 v48, v2
	v_mov_b32_e32 v49, v2
	v_mov_b32_e32 v54, v2
	v_mov_b32_e32 v55, v2
	v_mov_b32_e32 v56, v2
	v_mov_b32_e32 v57, v2
	v_mov_b32_e32 v10, v2
	v_mov_b32_e32 v11, v2
	v_mov_b32_e32 v12, v2
	v_mov_b32_e32 v13, v2
	v_mov_b32_e32 v18, v2
	v_mov_b32_e32 v19, v2
	v_mov_b32_e32 v20, v2
	v_mov_b32_e32 v21, v2
	v_mov_b32_e32 v26, v2
	v_mov_b32_e32 v27, v2
	v_mov_b32_e32 v28, v2
	v_mov_b32_e32 v29, v2
	v_mov_b32_e32 v34, v2
	v_mov_b32_e32 v35, v2
	v_mov_b32_e32 v36, v2
	v_mov_b32_e32 v37, v2
	v_mov_b32_e32 v42, v2
	v_mov_b32_e32 v43, v2
	v_mov_b32_e32 v44, v2
	v_mov_b32_e32 v45, v2
	v_mov_b32_e32 v50, v2
	v_mov_b32_e32 v51, v2
	v_mov_b32_e32 v52, v2
	v_mov_b32_e32 v53, v2
	v_mov_b32_e32 v58, v2
	v_mov_b32_e32 v59, v2
	v_mov_b32_e32 v60, v2
	v_mov_b32_e32 v61, v2
	v_mov_b32_e32 v62, v2
	v_mov_b32_e32 v63, v2
	v_mov_b32_e32 v64, v2
	v_mov_b32_e32 v65, v2
	v_mov_b32_e32 v66, v2
	v_mov_b32_e32 v67, v2
	v_mov_b32_e32 v68, v2
	v_mov_b32_e32 v69, v2
	v_mov_b32_e32 v70, v2
	v_mov_b32_e32 v71, v2
	v_mov_b32_e32 v72, v2
	v_mov_b32_e32 v73, v2
	v_mov_b32_e32 v84, v2
	v_mov_b32_e32 v85, v2
	v_mov_b32_e32 v86, v2
	v_mov_b32_e32 v87, v2
	v_mov_b32_e32 v92, v2
	v_mov_b32_e32 v93, v2
	v_mov_b32_e32 v94, v2
	v_mov_b32_e32 v95, v2
	v_mov_b32_e32 v100, v2
	v_mov_b32_e32 v101, v2
	v_mov_b32_e32 v102, v2
	v_mov_b32_e32 v103, v2
	v_mov_b32_e32 v108, v2
	v_mov_b32_e32 v109, v2
	v_mov_b32_e32 v110, v2
	v_mov_b32_e32 v111, v2
	v_mov_b32_e32 v116, v2
	v_mov_b32_e32 v117, v2
	v_mov_b32_e32 v118, v2
	v_mov_b32_e32 v119, v2
	v_mov_b32_e32 v124, v2
	v_mov_b32_e32 v125, v2
	v_mov_b32_e32 v126, v2
	v_mov_b32_e32 v127, v2
	v_mov_b32_e32 v74, v2
	v_mov_b32_e32 v75, v2
	v_mov_b32_e32 v76, v2
	v_mov_b32_e32 v77, v2
	v_mov_b32_e32 v88, v2
	v_mov_b32_e32 v89, v2
	v_mov_b32_e32 v90, v2
	v_mov_b32_e32 v91, v2
	v_mov_b32_e32 v96, v2
	v_mov_b32_e32 v97, v2
	v_mov_b32_e32 v98, v2
	v_mov_b32_e32 v99, v2
	v_mov_b32_e32 v104, v2
	v_mov_b32_e32 v105, v2
	v_mov_b32_e32 v106, v2
	v_mov_b32_e32 v107, v2
	v_mov_b32_e32 v112, v2
	v_mov_b32_e32 v113, v2
	v_mov_b32_e32 v114, v2
	v_mov_b32_e32 v115, v2
	v_mov_b32_e32 v120, v2
	v_mov_b32_e32 v121, v2
	v_mov_b32_e32 v122, v2
	v_mov_b32_e32 v123, v2
	v_mov_b32_e32 v128, v2
	v_mov_b32_e32 v129, v2
	v_mov_b32_e32 v130, v2
	v_mov_b32_e32 v131, v2
	v_mov_b32_e32 v132, v2
	v_mov_b32_e32 v133, v2
	v_mov_b32_e32 v134, v2
	v_mov_b32_e32 v135, v2

; template <class Epi, class Sched, bool ALIGN_EPI = false, bool SP2 = false>
; __device__ __forceinline__ void gemm_phase(PG8_LAS unsigned char* lds, const Gemm g, const Sched& S, const Epi& E) {
;     ...
;         for (int t = 0; t < nt; t += 2) {
;             const bool last = (t == nt - 2);
;             const char* a1 = cA + (size_t)(t + 1) * kstep;
;             const char* a2 = last ? nA : cA + (size_t)(t + 2) * kstep; const char* b2 = last ? nB : cB + (size_t)(t + 2) * kstep;
;             const char* a3 = a2 + kstep; const char* b3 = b2 + kstep;
;     ...
; #pragma unroll
;         for (int a = 0; a < 2; ++a)
; #pragma unroll
;             for (int b = 0; b < 2; ++b)
; #pragma unroll
;                 for (int m = 0; m < 4; ++m)
; #pragma unroll
;                     for (int n = 0; n < 2; ++n) acc[a][b][m][n] = (f32x4){0.f, 0.f, 0.f, 0.f};
.LBB0_526:
	s_add_u32 s42, s42, 0x80
	s_addc_u32 s43, s43, 0
	s_add_u32 s87, s72, 0x100
	v_mov_b32_e32 v2, 0
	s_addc_u32 s88, s73, 0
	s_mov_b32 s72, 0
	v_mov_b32_e32 v3, v2
	v_mov_b32_e32 v4, v2
	v_mov_b32_e32 v5, v2
	v_mov_b32_e32 v6, v2
	v_mov_b32_e32 v7, v2
	v_mov_b32_e32 v8, v2
	v_mov_b32_e32 v9, v2
	v_mov_b32_e32 v18, v2
	v_mov_b32_e32 v19, v2
	v_mov_b32_e32 v20, v2
	v_mov_b32_e32 v21, v2
	v_mov_b32_e32 v22, v2
	v_mov_b32_e32 v23, v2
	v_mov_b32_e32 v24, v2
	v_mov_b32_e32 v25, v2
	v_mov_b32_e32 v34, v2
	v_mov_b32_e32 v35, v2
	v_mov_b32_e32 v36, v2
	v_mov_b32_e32 v37, v2
	v_mov_b32_e32 v38, v2
	v_mov_b32_e32 v39, v2
	v_mov_b32_e32 v40, v2
	v_mov_b32_e32 v41, v2
	v_mov_b32_e32 v50, v2
	v_mov_b32_e32 v51, v2
	v_mov_b32_e32 v52, v2
	v_mov_b32_e32 v53, v2
	v_mov_b32_e32 v54, v2
	v_mov_b32_e32 v55, v2
	v_mov_b32_e32 v56, v2
	v_mov_b32_e32 v57, v2
	v_mov_b32_e32 v10, v2
	v_mov_b32_e32 v11, v2
	v_mov_b32_e32 v12, v2
	v_mov_b32_e32 v13, v2
	v_mov_b32_e32 v14, v2
	v_mov_b32_e32 v15, v2
	v_mov_b32_e32 v16, v2
	v_mov_b32_e32 v17, v2
	v_mov_b32_e32 v26, v2
	v_mov_b32_e32 v27, v2
	v_mov_b32_e32 v28, v2
	v_mov_b32_e32 v29, v2
	v_mov_b32_e32 v30, v2
	v_mov_b32_e32 v31, v2
	v_mov_b32_e32 v32, v2
	v_mov_b32_e32 v33, v2
	v_mov_b32_e32 v42, v2
	v_mov_b32_e32 v43, v2
	v_mov_b32_e32 v44, v2
	v_mov_b32_e32 v45, v2
	v_mov_b32_e32 v46, v2
	v_mov_b32_e32 v47, v2
	v_mov_b32_e32 v48, v2
	v_mov_b32_e32 v49, v2
	v_mov_b32_e32 v58, v2
	v_mov_b32_e32 v59, v2
	v_mov_b32_e32 v60, v2
	v_mov_b32_e32 v61, v2
	v_mov_b32_e32 v62, v2
	v_mov_b32_e32 v63, v2
	v_mov_b32_e32 v64, v2
	v_mov_b32_e32 v65, v2
	v_mov_b32_e32 v66, v2
	v_mov_b32_e32 v67, v2
	v_mov_b32_e32 v68, v2
	v_mov_b32_e32 v69, v2
	v_mov_b32_e32 v70, v2
	v_mov_b32_e32 v71, v2
	v_mov_b32_e32 v72, v2
	v_mov_b32_e32 v73, v2
	v_mov_b32_e32 v88, v2
	v_mov_b32_e32 v89, v2
	v_mov_b32_e32 v90, v2
	v_mov_b32_e32 v91, v2
	v_mov_b32_e32 v92, v2
	v_mov_b32_e32 v93, v2
	v_mov_b32_e32 v94, v2
	v_mov_b32_e32 v95, v2
	v_mov_b32_e32 v104, v2
	v_mov_b32_e32 v105, v2
	v_mov_b32_e32 v106, v2
	v_mov_b32_e32 v107, v2
	v_mov_b32_e32 v108, v2
	v_mov_b32_e32 v109, v2
	v_mov_b32_e32 v110, v2
	v_mov_b32_e32 v111, v2
	v_mov_b32_e32 v120, v2
	v_mov_b32_e32 v121, v2
	v_mov_b32_e32 v122, v2
	v_mov_b32_e32 v123, v2
	v_mov_b32_e32 v124, v2
	v_mov_b32_e32 v125, v2
	v_mov_b32_e32 v126, v2
	v_mov_b32_e32 v127, v2
	v_mov_b32_e32 v74, v2
	v_mov_b32_e32 v75, v2
	v_mov_b32_e32 v76, v2
	v_mov_b32_e32 v77, v2
	v_mov_b32_e32 v84, v2
	v_mov_b32_e32 v85, v2
	v_mov_b32_e32 v86, v2
	v_mov_b32_e32 v87, v2
	v_mov_b32_e32 v96, v2
	v_mov_b32_e32 v97, v2
	v_mov_b32_e32 v98, v2
	v_mov_b32_e32 v99, v2
	v_mov_b32_e32 v100, v2
	v_mov_b32_e32 v101, v2
	v_mov_b32_e32 v102, v2
	v_mov_b32_e32 v103, v2
	v_mov_b32_e32 v112, v2
	v_mov_b32_e32 v113, v2
	v_mov_b32_e32 v114, v2
	v_mov_b32_e32 v115, v2
	v_mov_b32_e32 v116, v2
	v_mov_b32_e32 v117, v2
	v_mov_b32_e32 v118, v2
	v_mov_b32_e32 v119, v2
	v_mov_b32_e32 v128, v2
	v_mov_b32_e32 v129, v2
	v_mov_b32_e32 v130, v2
	v_mov_b32_e32 v131, v2
	v_mov_b32_e32 v132, v2
	v_mov_b32_e32 v133, v2
	v_mov_b32_e32 v134, v2
	v_mov_b32_e32 v135, v2

; template <class Epi, class Sched, bool ALIGN_EPI = false, bool SP2 = false>
; __device__ __forceinline__ void gemm_phase(PG8_LAS unsigned char* lds, const Gemm g, const Sched& S, const Epi& E) {
;     ...
;         const bool has_next = S.next(ui + 1, nxt);
;         const char* nA = has_next ? (const char*)g.A + (size_t)nxt.pm * tstepA : cA; const char* nB = has_next ? (const char*)g.Bt + (size_t)nxt.pn * tstep : cB;
;         for (int t = 0; t < nt; t += 2) {
;             const bool last = (t == nt - 2);
;             const char* a1 = cA + (size_t)(t + 1) * kstep;
;             const char* a2 = last ? nA : cA + (size_t)(t + 2) * kstep; const char* b2 = last ? nB : cB + (size_t)(t + 2) * kstep;
;             const char* a3 = a2 + kstep; const char* b3 = b2 + kstep;
;     ...
; #pragma unroll
;         for (int a = 0; a < 2; ++a)
; #pragma unroll
;             for (int b = 0; b < 2; ++b)
; #pragma unroll
;                 for (int m = 0; m < 4; ++m)
; #pragma unroll
;                     for (int n = 0; n < 2; ++n) acc[a][b][m][n] = (f32x4){0.f, 0.f, 0.f, 0.f};
.LBB0_635:
	s_ashr_i32 s19, s18, 31
	s_lshl_b64 s[20:21], s[18:19], 19
	s_add_u32 s20, s30, s20
	s_addc_u32 s21, s31, s21
	s_and_b64 s[24:25], s[40:41], exec
	s_cselect_b32 s19, s21, s43
	s_cselect_b32 s55, s20, s42
	s_ashr_i32 s11, s10, 31
	s_lshl_b64 s[24:25], s[10:11], 19
	s_add_u32 s24, s51, s24
	s_addc_u32 s25, s52, s25
	s_and_b64 s[46:47], s[40:41], exec
	s_cselect_b32 s11, s25, s45
	s_cselect_b32 s56, s24, s44
	s_add_u32 s42, s42, 0x40080
	s_addc_u32 s43, s43, 0
	s_add_u32 s57, s44, 0x100
	v_mov_b32_e32 v2, 0
	s_addc_u32 s58, s45, 0
	s_mov_b32 s59, -2
	v_mov_b32_e32 v3, v2
	v_mov_b32_e32 v4, v2
	v_mov_b32_e32 v5, v2
	v_mov_b32_e32 v6, v2
	v_mov_b32_e32 v7, v2
	v_mov_b32_e32 v8, v2
	v_mov_b32_e32 v9, v2
	v_mov_b32_e32 v18, v2
	v_mov_b32_e32 v19, v2
	v_mov_b32_e32 v20, v2
	v_mov_b32_e32 v21, v2
	v_mov_b32_e32 v22, v2
	v_mov_b32_e32 v23, v2
	v_mov_b32_e32 v24, v2
	v_mov_b32_e32 v25, v2
	v_mov_b32_e32 v34, v2
	v_mov_b32_e32 v35, v2
	v_mov_b32_e32 v36, v2
	v_mov_b32_e32 v37, v2
	v_mov_b32_e32 v38, v2
	v_mov_b32_e32 v39, v2
	v_mov_b32_e32 v40, v2
	v_mov_b32_e32 v41, v2
	v_mov_b32_e32 v50, v2
	v_mov_b32_e32 v51, v2
	v_mov_b32_e32 v52, v2
	v_mov_b32_e32 v53, v2
	v_mov_b32_e32 v54, v2
	v_mov_b32_e32 v55, v2
	v_mov_b32_e32 v56, v2
	v_mov_b32_e32 v57, v2
	v_mov_b32_e32 v10, v2
	v_mov_b32_e32 v11, v2
	v_mov_b32_e32 v12, v2
	v_mov_b32_e32 v13, v2
	v_mov_b32_e32 v14, v2
	v_mov_b32_e32 v15, v2
	v_mov_b32_e32 v16, v2
	v_mov_b32_e32 v17, v2
	v_mov_b32_e32 v26, v2
	v_mov_b32_e32 v27, v2
	v_mov_b32_e32 v28, v2
	v_mov_b32_e32 v29, v2
	v_mov_b32_e32 v30, v2
	v_mov_b32_e32 v31, v2
	v_mov_b32_e32 v32, v2
	v_mov_b32_e32 v33, v2
	v_mov_b32_e32 v42, v2
	v_mov_b32_e32 v43, v2
	v_mov_b32_e32 v44, v2
	v_mov_b32_e32 v45, v2
	v_mov_b32_e32 v46, v2
	v_mov_b32_e32 v47, v2
	v_mov_b32_e32 v48, v2
	v_mov_b32_e32 v49, v2
	v_mov_b32_e32 v58, v2
	v_mov_b32_e32 v59, v2
	v_mov_b32_e32 v60, v2
	v_mov_b32_e32 v61, v2
	v_mov_b32_e32 v62, v2
	v_mov_b32_e32 v63, v2
	v_mov_b32_e32 v64, v2
	v_mov_b32_e32 v65, v2
	v_mov_b32_e32 v66, v2
	v_mov_b32_e32 v67, v2
	v_mov_b32_e32 v68, v2
	v_mov_b32_e32 v69, v2
	v_mov_b32_e32 v70, v2
	v_mov_b32_e32 v71, v2
	v_mov_b32_e32 v72, v2
	v_mov_b32_e32 v73, v2
	v_mov_b32_e32 v88, v2
	v_mov_b32_e32 v89, v2
	v_mov_b32_e32 v90, v2
	v_mov_b32_e32 v91, v2
	v_mov_b32_e32 v92, v2
	v_mov_b32_e32 v93, v2
	v_mov_b32_e32 v94, v2
	v_mov_b32_e32 v95, v2
	v_mov_b32_e32 v104, v2
	v_mov_b32_e32 v105, v2
	v_mov_b32_e32 v106, v2
	v_mov_b32_e32 v107, v2
	v_mov_b32_e32 v108, v2
	v_mov_b32_e32 v109, v2
	v_mov_b32_e32 v110, v2
	v_mov_b32_e32 v111, v2
	v_mov_b32_e32 v120, v2
	v_mov_b32_e32 v121, v2
	v_mov_b32_e32 v122, v2
	v_mov_b32_e32 v123, v2
	v_mov_b32_e32 v124, v2
	v_mov_b32_e32 v125, v2
	v_mov_b32_e32 v126, v2
	v_mov_b32_e32 v127, v2
	v_mov_b32_e32 v74, v2
	v_mov_b32_e32 v75, v2
	v_mov_b32_e32 v76, v2
	v_mov_b32_e32 v77, v2
	v_mov_b32_e32 v84, v2
	v_mov_b32_e32 v85, v2
	v_mov_b32_e32 v86, v2
	v_mov_b32_e32 v87, v2
	v_mov_b32_e32 v96, v2
	v_mov_b32_e32 v97, v2
	v_mov_b32_e32 v98, v2
	v_mov_b32_e32 v99, v2
	v_mov_b32_e32 v100, v2
	v_mov_b32_e32 v101, v2
	v_mov_b32_e32 v102, v2
	v_mov_b32_e32 v103, v2
	v_mov_b32_e32 v112, v2
	v_mov_b32_e32 v113, v2
	v_mov_b32_e32 v114, v2
	v_mov_b32_e32 v115, v2
	v_mov_b32_e32 v116, v2
	v_mov_b32_e32 v117, v2
	v_mov_b32_e32 v118, v2
	v_mov_b32_e32 v119, v2
	v_mov_b32_e32 v128, v2
	v_mov_b32_e32 v129, v2
	v_mov_b32_e32 v130, v2
	v_mov_b32_e32 v131, v2
	v_mov_b32_e32 v132, v2
	v_mov_b32_e32 v133, v2
	v_mov_b32_e32 v134, v2
	v_mov_b32_e32 v135, v2
